# attention fast loop: three iterations (six key tiles) per trip with constant LDS slot offsets (no per-step address VALU, no slot bookkeeping, one back edge per six tiles)
# speedup vs baseline: 1.0226x; 1.0069x over previous
.Lfast_disp:
	s_add_i32 s5, s10, 4
	s_cmp_lt_u32 s5, s19
	s_cbranch_scc0 .Lfast_485
.Lfast3:
.Lf3_0_485:
	ds_read_b64_tr_b16 v[178:179], v203 offset:24576
	ds_read_b64_tr_b16 v[180:181], v203 offset:25088
	s_waitcnt lgkmcnt(9)
	v_mfma_f32_32x32x16_bf16 v[98:113], v[174:177], v[142:145], v[34:49]
	v_add_f32_e32 v82, v66, v67
	v_add_f32_e32 v82, v68, v82
	v_add_f32_e32 v82, v69, v82
	v_add_f32_e32 v82, v70, v82
	v_add_f32_e32 v82, v71, v82
	v_cvt_pk_bf16_f32 v138, v66, v67
	v_cvt_pk_bf16_f32 v139, v68, v69
	ds_read_b64_tr_b16 v[174:175], v203 offset:28672
	ds_read_b64_tr_b16 v[176:177], v203 offset:29184
	v_add_f32_e32 v66, v72, v82
	s_waitcnt lgkmcnt(10)
	v_mfma_f32_32x32x16_bf16 v[82:97], v[170:173], v[142:145], v[34:49]
	v_add_f32_e32 v66, v73, v66
	v_add_f32_e32 v66, v74, v66
	v_add_f32_e32 v114, v75, v66
	v_cvt_pk_bf16_f32 v140, v70, v71
	v_cvt_pk_bf16_f32 v141, v72, v73
	ds_read_b64_tr_b16 v[66:67], v203 offset:25600
	ds_read_b64_tr_b16 v[68:69], v203 offset:26112
	s_waitcnt lgkmcnt(11)
	v_mfma_f32_32x32x16_bf16 v[98:113], v[166:169], v[134:137], v[98:113]
	v_add_f32_e32 v70, v76, v114
	v_add_f32_e32 v70, v77, v70
	v_add_f32_e32 v70, v78, v70
	v_add_f32_e32 v114, v79, v70
	v_cvt_pk_bf16_f32 v130, v74, v75
	v_cvt_pk_bf16_f32 v131, v76, v77
	ds_read_b64_tr_b16 v[70:71], v203 offset:29696
	ds_read_b64_tr_b16 v[72:73], v203 offset:30208
	s_waitcnt lgkmcnt(12)
	v_mfma_f32_32x32x16_bf16 v[82:97], v[162:165], v[134:137], v[82:97]
	v_add_f32_e32 v74, v80, v114
	v_add_f32_e32 v74, v81, v74
	v_add_f32_e32 v74, v50, v74
	v_add_f32_e32 v114, v51, v74
	v_cvt_pk_bf16_f32 v132, v78, v79
	v_cvt_pk_bf16_f32 v133, v80, v81
	ds_read_b64_tr_b16 v[74:75], v203 offset:26624
	ds_read_b64_tr_b16 v[76:77], v203 offset:27136
	s_waitcnt lgkmcnt(13)
	v_mfma_f32_32x32x16_bf16 v[98:113], v[158:161], v[126:129], v[98:113]
	v_add_f32_e32 v78, v52, v114
	v_add_f32_e32 v78, v53, v78
	v_add_f32_e32 v78, v54, v78
	v_add_f32_e32 v78, v55, v78
	v_cvt_pk_bf16_f32 v122, v50, v51
	v_cvt_pk_bf16_f32 v123, v52, v53
	ds_read_b64_tr_b16 v[50:51], v203 offset:30720
	ds_read_b64_tr_b16 v[52:53], v203 offset:31232
	s_waitcnt lgkmcnt(14)
	v_mfma_f32_32x32x16_bf16 v[82:97], v[154:157], v[126:129], v[82:97]
	v_add_f32_e32 v78, v56, v78
	v_add_f32_e32 v78, v57, v78
	v_add_f32_e32 v78, v58, v78
	v_add_f32_e32 v78, v59, v78
	v_cvt_pk_bf16_f32 v124, v54, v55
	v_cvt_pk_bf16_f32 v125, v56, v57
	ds_read_b64_tr_b16 v[54:55], v203 offset:27648
	ds_read_b64_tr_b16 v[56:57], v203 offset:28160
	s_waitcnt lgkmcnt(14)
	v_mfma_f32_32x32x16_bf16 v[98:113], v[150:153], v[118:121], v[98:113]
	v_add_f32_e32 v78, v60, v78
	v_add_f32_e32 v78, v61, v78
	v_add_f32_e32 v78, v62, v78
	v_add_f32_e32 v78, v63, v78
	v_cvt_pk_bf16_f32 v114, v58, v59
	v_cvt_pk_bf16_f32 v115, v60, v61
	ds_read_b64_tr_b16 v[58:59], v203 offset:31744
	ds_read_b64_tr_b16 v[60:61], v203 offset:32256
	v_mfma_f32_32x32x16_bf16 v[82:97], v[146:149], v[118:121], v[82:97]
	v_add_f32_e32 v78, v64, v78
	v_add_f32_e32 v78, v65, v78
	v_cvt_pk_bf16_f32 v116, v62, v63
	v_cvt_pk_bf16_f32 v117, v64, v65
	s_add_i32 s98, s46, 0x2000
	s_mov_b32 s5, m0
	s_mov_b32 m0, s98
	s_nop 0
	global_load_lds_dwordx4 v188, s[100:101]
	s_mov_b32 m0, s5
	s_add_i32 s98, s47, 0x4000
	s_mov_b32 s5, m0
	s_mov_b32 m0, s98
	s_nop 0
	global_load_lds_dwordx4 v186, s[100:101]
	s_mov_b32 m0, s5
	v_add_f32_e32 v190, v205, v78
.Lf3_0_486:
	s_waitcnt lgkmcnt(14)
	v_mfma_f32_32x32x16_bf16 v[18:33], v[138:141], v[178:181], v[18:33]
	v_exp_f32_e32 v98, v98
	v_exp_f32_e32 v99, v99
	v_exp_f32_e32 v100, v100
	v_exp_f32_e32 v101, v101
	s_waitcnt lgkmcnt(12)
	v_mfma_f32_32x32x16_bf16 v[2:17], v[138:141], v[174:177], v[2:17]
	v_exp_f32_e32 v102, v102
	v_exp_f32_e32 v103, v103
	v_exp_f32_e32 v104, v104
	v_exp_f32_e32 v105, v105
	ds_read_b128 v[62:65], v202 offset:16384
	ds_read_b128 v[174:177], v202 offset:16896
	s_waitcnt lgkmcnt(12)
	v_mfma_f32_32x32x16_bf16 v[18:33], v[130:133], v[66:69], v[18:33]
	v_exp_f32_e32 v106, v106
	v_exp_f32_e32 v107, v107
	v_exp_f32_e32 v108, v108
	v_exp_f32_e32 v109, v109
	ds_read_b128 v[178:181], v202 offset:18432
	ds_read_b128 v[170:173], v202 offset:18944
	s_waitcnt lgkmcnt(12)
	v_mfma_f32_32x32x16_bf16 v[2:17], v[130:133], v[70:73], v[2:17]
	v_exp_f32_e32 v110, v110
	v_exp_f32_e32 v111, v111
	v_exp_f32_e32 v112, v112
	v_exp_f32_e32 v113, v113
	ds_read_b128 v[166:169], v202 offset:20480
	ds_read_b128 v[162:165], v202 offset:20992
	s_waitcnt lgkmcnt(12)
	v_mfma_f32_32x32x16_bf16 v[18:33], v[122:125], v[74:77], v[18:33]
	v_exp_f32_e32 v82, v82
	v_exp_f32_e32 v83, v83
	v_exp_f32_e32 v84, v84
	v_exp_f32_e32 v85, v85
	ds_read_b128 v[158:161], v202 offset:22528
	ds_read_b128 v[154:157], v202 offset:23040
	s_waitcnt lgkmcnt(12)
	v_mfma_f32_32x32x16_bf16 v[2:17], v[122:125], v[50:53], v[2:17]
	v_exp_f32_e32 v86, v86
	v_exp_f32_e32 v87, v87
	v_exp_f32_e32 v88, v88
	v_exp_f32_e32 v89, v89
	s_waitcnt lgkmcnt(10)
	v_mfma_f32_32x32x16_bf16 v[18:33], v[114:117], v[54:57], v[18:33]
	v_exp_f32_e32 v90, v90
	v_exp_f32_e32 v91, v91
	v_exp_f32_e32 v92, v92
	v_exp_f32_e32 v93, v93
	s_waitcnt lgkmcnt(8)
	v_mfma_f32_32x32x16_bf16 v[2:17], v[114:117], v[58:61], v[2:17]
	v_exp_f32_e32 v94, v94
	v_exp_f32_e32 v95, v95
	v_exp_f32_e32 v96, v96
	v_exp_f32_e32 v97, v97
	s_waitcnt vmcnt(2) lgkmcnt(0)
	s_barrier
.Lf3_0_488:
	ds_read_b64_tr_b16 v[150:151], v203 offset:32768
	ds_read_b64_tr_b16 v[152:153], v203 offset:33280
	s_waitcnt lgkmcnt(9)
	v_mfma_f32_32x32x16_bf16 v[66:81], v[62:65], v[142:145], v[34:49]
	v_add_f32_e32 v50, v98, v99
	v_add_f32_e32 v50, v100, v50
	v_add_f32_e32 v50, v101, v50
	v_add_f32_e32 v50, v102, v50
	v_add_f32_e32 v50, v103, v50
	v_cvt_pk_bf16_f32 v138, v98, v99
	v_cvt_pk_bf16_f32 v139, v100, v101
	ds_read_b64_tr_b16 v[146:147], v203 offset:36864
	ds_read_b64_tr_b16 v[148:149], v203 offset:37376
	v_add_f32_e32 v50, v104, v50
	v_add_f32_e32 v50, v105, v50
	v_add_f32_e32 v50, v106, v50
	v_add_f32_e32 v114, v107, v50
	s_waitcnt lgkmcnt(10)
	v_mfma_f32_32x32x16_bf16 v[50:65], v[174:177], v[142:145], v[34:49]
	v_cvt_pk_bf16_f32 v140, v102, v103
	v_cvt_pk_bf16_f32 v141, v104, v105
	ds_read_b64_tr_b16 v[98:99], v203 offset:33792
	ds_read_b64_tr_b16 v[100:101], v203 offset:34304
	s_waitcnt lgkmcnt(11)
	v_mfma_f32_32x32x16_bf16 v[66:81], v[178:181], v[134:137], v[66:81]
	v_add_f32_e32 v102, v108, v114
	v_add_f32_e32 v102, v109, v102
	v_add_f32_e32 v102, v110, v102
	v_add_f32_e32 v114, v111, v102
	v_cvt_pk_bf16_f32 v130, v106, v107
	v_cvt_pk_bf16_f32 v131, v108, v109
	ds_read_b64_tr_b16 v[102:103], v203 offset:37888
	ds_read_b64_tr_b16 v[104:105], v203 offset:38400
	s_waitcnt lgkmcnt(12)
	v_mfma_f32_32x32x16_bf16 v[50:65], v[170:173], v[134:137], v[50:65]
	v_add_f32_e32 v106, v112, v114
	v_add_f32_e32 v106, v113, v106
	v_add_f32_e32 v106, v82, v106
	v_add_f32_e32 v114, v83, v106
	v_cvt_pk_bf16_f32 v132, v110, v111
	v_cvt_pk_bf16_f32 v133, v112, v113
	ds_read_b64_tr_b16 v[106:107], v203 offset:34816
	ds_read_b64_tr_b16 v[108:109], v203 offset:35328
	s_waitcnt lgkmcnt(13)
	v_mfma_f32_32x32x16_bf16 v[66:81], v[166:169], v[126:129], v[66:81]
	v_add_f32_e32 v110, v84, v114
	v_add_f32_e32 v110, v85, v110
	v_add_f32_e32 v110, v86, v110
	v_add_f32_e32 v110, v87, v110
	v_cvt_pk_bf16_f32 v122, v82, v83
	v_cvt_pk_bf16_f32 v123, v84, v85
	ds_read_b64_tr_b16 v[82:83], v203 offset:38912
	ds_read_b64_tr_b16 v[84:85], v203 offset:39424
	s_waitcnt lgkmcnt(14)
	v_mfma_f32_32x32x16_bf16 v[50:65], v[162:165], v[126:129], v[50:65]
	v_add_f32_e32 v110, v88, v110
	v_add_f32_e32 v110, v89, v110
	v_add_f32_e32 v110, v90, v110
	v_add_f32_e32 v110, v91, v110
	v_cvt_pk_bf16_f32 v124, v86, v87
	v_cvt_pk_bf16_f32 v125, v88, v89
	ds_read_b64_tr_b16 v[86:87], v203 offset:35840
	ds_read_b64_tr_b16 v[88:89], v203 offset:36352
	s_waitcnt lgkmcnt(14)
	v_mfma_f32_32x32x16_bf16 v[66:81], v[158:161], v[118:121], v[66:81]
	v_add_f32_e32 v110, v92, v110
	v_add_f32_e32 v110, v93, v110
	v_add_f32_e32 v110, v94, v110
	v_add_f32_e32 v110, v95, v110
	v_cvt_pk_bf16_f32 v114, v90, v91
	v_cvt_pk_bf16_f32 v115, v92, v93
	ds_read_b64_tr_b16 v[90:91], v203 offset:39936
	ds_read_b64_tr_b16 v[92:93], v203 offset:40448
	v_mfma_f32_32x32x16_bf16 v[50:65], v[154:157], v[118:121], v[50:65]
	v_add_f32_e32 v110, v96, v110
	v_add_f32_e32 v110, v97, v110
	v_cvt_pk_bf16_f32 v116, v94, v95
	v_cvt_pk_bf16_f32 v117, v96, v97
	s_add_i32 s98, s46, 0x4000
	s_mov_b32 s5, m0
	s_mov_b32 m0, s98
	s_nop 0
	global_load_lds_dwordx4 v189, s[100:101]
	s_mov_b32 m0, s5
	s_add_i32 s98, s47, 0x0
	s_mov_b32 s5, m0
	s_mov_b32 m0, s98
	s_nop 0
	global_load_lds_dwordx4 v187, s[100:101]
	s_mov_b32 m0, s5
	v_add_f32_e32 v205, v190, v110
.Lf3_0_489:
	s_waitcnt lgkmcnt(14)
	v_mfma_f32_32x32x16_bf16 v[18:33], v[138:141], v[150:153], v[18:33]
	v_exp_f32_e32 v66, v66
	v_exp_f32_e32 v67, v67
	v_exp_f32_e32 v68, v68
	v_exp_f32_e32 v69, v69
	s_waitcnt lgkmcnt(12)
	v_mfma_f32_32x32x16_bf16 v[2:17], v[138:141], v[146:149], v[2:17]
	v_exp_f32_e32 v70, v70
	v_exp_f32_e32 v71, v71
	v_exp_f32_e32 v72, v72
	v_exp_f32_e32 v73, v73
	ds_read_b128 v[174:177], v202 offset:0
	ds_read_b128 v[170:173], v202 offset:512
	s_waitcnt lgkmcnt(12)
	v_mfma_f32_32x32x16_bf16 v[18:33], v[130:133], v[98:101], v[18:33]
	v_exp_f32_e32 v74, v74
	v_exp_f32_e32 v75, v75
	v_exp_f32_e32 v76, v76
	v_exp_f32_e32 v77, v77
	ds_read_b128 v[166:169], v202 offset:2048
	ds_read_b128 v[162:165], v202 offset:2560
	s_waitcnt lgkmcnt(12)
	v_mfma_f32_32x32x16_bf16 v[2:17], v[130:133], v[102:105], v[2:17]
	v_exp_f32_e32 v78, v78
	v_exp_f32_e32 v79, v79
	v_exp_f32_e32 v80, v80
	v_exp_f32_e32 v81, v81
	ds_read_b128 v[158:161], v202 offset:4096
	ds_read_b128 v[154:157], v202 offset:4608
	s_waitcnt lgkmcnt(12)
	v_mfma_f32_32x32x16_bf16 v[18:33], v[122:125], v[106:109], v[18:33]
	v_exp_f32_e32 v50, v50
	v_exp_f32_e32 v51, v51
	v_exp_f32_e32 v52, v52
	v_exp_f32_e32 v53, v53
	ds_read_b128 v[150:153], v202 offset:6144
	ds_read_b128 v[146:149], v202 offset:6656
	s_waitcnt lgkmcnt(12)
	v_mfma_f32_32x32x16_bf16 v[2:17], v[122:125], v[82:85], v[2:17]
	v_exp_f32_e32 v54, v54
	v_exp_f32_e32 v55, v55
	v_exp_f32_e32 v56, v56
	v_exp_f32_e32 v57, v57
	s_waitcnt lgkmcnt(10)
	v_mfma_f32_32x32x16_bf16 v[18:33], v[114:117], v[86:89], v[18:33]
	v_exp_f32_e32 v58, v58
	v_exp_f32_e32 v59, v59
	v_exp_f32_e32 v60, v60
	v_exp_f32_e32 v61, v61
	s_waitcnt lgkmcnt(8)
	v_mfma_f32_32x32x16_bf16 v[2:17], v[114:117], v[90:93], v[2:17]
	v_exp_f32_e32 v62, v62
	v_exp_f32_e32 v63, v63
	v_exp_f32_e32 v64, v64
	v_exp_f32_e32 v65, v65
	s_waitcnt vmcnt(2) lgkmcnt(0)
	s_barrier

.Lf3_1_485:
	ds_read_b64_tr_b16 v[178:179], v203 offset:40960
	ds_read_b64_tr_b16 v[180:181], v203 offset:41472
	s_waitcnt lgkmcnt(9)
	v_mfma_f32_32x32x16_bf16 v[98:113], v[174:177], v[142:145], v[34:49]
	v_add_f32_e32 v82, v66, v67
	v_add_f32_e32 v82, v68, v82
	v_add_f32_e32 v82, v69, v82
	v_add_f32_e32 v82, v70, v82
	v_add_f32_e32 v82, v71, v82
	v_cvt_pk_bf16_f32 v138, v66, v67
	v_cvt_pk_bf16_f32 v139, v68, v69
	ds_read_b64_tr_b16 v[174:175], v203 offset:45056
	ds_read_b64_tr_b16 v[176:177], v203 offset:45568
	v_add_f32_e32 v66, v72, v82
	s_waitcnt lgkmcnt(10)
	v_mfma_f32_32x32x16_bf16 v[82:97], v[170:173], v[142:145], v[34:49]
	v_add_f32_e32 v66, v73, v66
	v_add_f32_e32 v66, v74, v66
	v_add_f32_e32 v114, v75, v66
	v_cvt_pk_bf16_f32 v140, v70, v71
	v_cvt_pk_bf16_f32 v141, v72, v73
	ds_read_b64_tr_b16 v[66:67], v203 offset:41984
	ds_read_b64_tr_b16 v[68:69], v203 offset:42496
	s_waitcnt lgkmcnt(11)
	v_mfma_f32_32x32x16_bf16 v[98:113], v[166:169], v[134:137], v[98:113]
	v_add_f32_e32 v70, v76, v114
	v_add_f32_e32 v70, v77, v70
	v_add_f32_e32 v70, v78, v70
	v_add_f32_e32 v114, v79, v70
	v_cvt_pk_bf16_f32 v130, v74, v75
	v_cvt_pk_bf16_f32 v131, v76, v77
	ds_read_b64_tr_b16 v[70:71], v203 offset:46080
	ds_read_b64_tr_b16 v[72:73], v203 offset:46592
	s_waitcnt lgkmcnt(12)
	v_mfma_f32_32x32x16_bf16 v[82:97], v[162:165], v[134:137], v[82:97]
	v_add_f32_e32 v74, v80, v114
	v_add_f32_e32 v74, v81, v74
	v_add_f32_e32 v74, v50, v74
	v_add_f32_e32 v114, v51, v74
	v_cvt_pk_bf16_f32 v132, v78, v79
	v_cvt_pk_bf16_f32 v133, v80, v81
	ds_read_b64_tr_b16 v[74:75], v203 offset:43008
	ds_read_b64_tr_b16 v[76:77], v203 offset:43520
	s_waitcnt lgkmcnt(13)
	v_mfma_f32_32x32x16_bf16 v[98:113], v[158:161], v[126:129], v[98:113]
	v_add_f32_e32 v78, v52, v114
	v_add_f32_e32 v78, v53, v78
	v_add_f32_e32 v78, v54, v78
	v_add_f32_e32 v78, v55, v78
	v_cvt_pk_bf16_f32 v122, v50, v51
	v_cvt_pk_bf16_f32 v123, v52, v53
	ds_read_b64_tr_b16 v[50:51], v203 offset:47104
	ds_read_b64_tr_b16 v[52:53], v203 offset:47616
	s_waitcnt lgkmcnt(14)
	v_mfma_f32_32x32x16_bf16 v[82:97], v[154:157], v[126:129], v[82:97]
	v_add_f32_e32 v78, v56, v78
	v_add_f32_e32 v78, v57, v78
	v_add_f32_e32 v78, v58, v78
	v_add_f32_e32 v78, v59, v78
	v_cvt_pk_bf16_f32 v124, v54, v55
	v_cvt_pk_bf16_f32 v125, v56, v57
	ds_read_b64_tr_b16 v[54:55], v203 offset:44032
	ds_read_b64_tr_b16 v[56:57], v203 offset:44544
	s_waitcnt lgkmcnt(14)
	v_mfma_f32_32x32x16_bf16 v[98:113], v[150:153], v[118:121], v[98:113]
	v_add_f32_e32 v78, v60, v78
	v_add_f32_e32 v78, v61, v78
	v_add_f32_e32 v78, v62, v78
	v_add_f32_e32 v78, v63, v78
	v_cvt_pk_bf16_f32 v114, v58, v59
	v_cvt_pk_bf16_f32 v115, v60, v61
	ds_read_b64_tr_b16 v[58:59], v203 offset:48128
	ds_read_b64_tr_b16 v[60:61], v203 offset:48640
	v_mfma_f32_32x32x16_bf16 v[82:97], v[146:149], v[118:121], v[82:97]
	v_add_f32_e32 v78, v64, v78
	v_add_f32_e32 v78, v65, v78
	v_cvt_pk_bf16_f32 v116, v62, v63
	v_cvt_pk_bf16_f32 v117, v64, v65
	s_add_i32 s98, s46, 0x0
	s_mov_b32 s5, m0
	s_mov_b32 m0, s98
	s_nop 0
	global_load_lds_dwordx4 v188, s[100:101]
	s_mov_b32 m0, s5
	s_add_i32 s98, s47, 0x2000
	s_mov_b32 s5, m0
	s_mov_b32 m0, s98
	s_nop 0
	global_load_lds_dwordx4 v186, s[100:101]
	s_mov_b32 m0, s5
	v_add_f32_e32 v190, v205, v78
.Lf3_1_486:
	s_waitcnt lgkmcnt(14)
	v_mfma_f32_32x32x16_bf16 v[18:33], v[138:141], v[178:181], v[18:33]
	v_exp_f32_e32 v98, v98
	v_exp_f32_e32 v99, v99
	v_exp_f32_e32 v100, v100
	v_exp_f32_e32 v101, v101
	s_waitcnt lgkmcnt(12)
	v_mfma_f32_32x32x16_bf16 v[2:17], v[138:141], v[174:177], v[2:17]
	v_exp_f32_e32 v102, v102
	v_exp_f32_e32 v103, v103
	v_exp_f32_e32 v104, v104
	v_exp_f32_e32 v105, v105
	ds_read_b128 v[62:65], v202 offset:8192
	ds_read_b128 v[174:177], v202 offset:8704
	s_waitcnt lgkmcnt(12)
	v_mfma_f32_32x32x16_bf16 v[18:33], v[130:133], v[66:69], v[18:33]
	v_exp_f32_e32 v106, v106
	v_exp_f32_e32 v107, v107
	v_exp_f32_e32 v108, v108
	v_exp_f32_e32 v109, v109
	ds_read_b128 v[178:181], v202 offset:10240
	ds_read_b128 v[170:173], v202 offset:10752
	s_waitcnt lgkmcnt(12)
	v_mfma_f32_32x32x16_bf16 v[2:17], v[130:133], v[70:73], v[2:17]
	v_exp_f32_e32 v110, v110
	v_exp_f32_e32 v111, v111
	v_exp_f32_e32 v112, v112
	v_exp_f32_e32 v113, v113
	ds_read_b128 v[166:169], v202 offset:12288
	ds_read_b128 v[162:165], v202 offset:12800
	s_waitcnt lgkmcnt(12)
	v_mfma_f32_32x32x16_bf16 v[18:33], v[122:125], v[74:77], v[18:33]
	v_exp_f32_e32 v82, v82
	v_exp_f32_e32 v83, v83
	v_exp_f32_e32 v84, v84
	v_exp_f32_e32 v85, v85
	ds_read_b128 v[158:161], v202 offset:14336
	ds_read_b128 v[154:157], v202 offset:14848
	s_waitcnt lgkmcnt(12)
	v_mfma_f32_32x32x16_bf16 v[2:17], v[122:125], v[50:53], v[2:17]
	v_exp_f32_e32 v86, v86
	v_exp_f32_e32 v87, v87
	v_exp_f32_e32 v88, v88
	v_exp_f32_e32 v89, v89
	s_waitcnt lgkmcnt(10)
	v_mfma_f32_32x32x16_bf16 v[18:33], v[114:117], v[54:57], v[18:33]
	v_exp_f32_e32 v90, v90
	v_exp_f32_e32 v91, v91
	v_exp_f32_e32 v92, v92
	v_exp_f32_e32 v93, v93
	s_waitcnt lgkmcnt(8)
	v_mfma_f32_32x32x16_bf16 v[2:17], v[114:117], v[58:61], v[2:17]
	v_exp_f32_e32 v94, v94
	v_exp_f32_e32 v95, v95
	v_exp_f32_e32 v96, v96
	v_exp_f32_e32 v97, v97
	s_waitcnt vmcnt(2) lgkmcnt(0)
	s_barrier
.Lf3_1_488:
	ds_read_b64_tr_b16 v[150:151], v203 offset:24576
	ds_read_b64_tr_b16 v[152:153], v203 offset:25088
	s_waitcnt lgkmcnt(9)
	v_mfma_f32_32x32x16_bf16 v[66:81], v[62:65], v[142:145], v[34:49]
	v_add_f32_e32 v50, v98, v99
	v_add_f32_e32 v50, v100, v50
	v_add_f32_e32 v50, v101, v50
	v_add_f32_e32 v50, v102, v50
	v_add_f32_e32 v50, v103, v50
	v_cvt_pk_bf16_f32 v138, v98, v99
	v_cvt_pk_bf16_f32 v139, v100, v101
	ds_read_b64_tr_b16 v[146:147], v203 offset:28672
	ds_read_b64_tr_b16 v[148:149], v203 offset:29184
	v_add_f32_e32 v50, v104, v50
	v_add_f32_e32 v50, v105, v50
	v_add_f32_e32 v50, v106, v50
	v_add_f32_e32 v114, v107, v50
	s_waitcnt lgkmcnt(10)
	v_mfma_f32_32x32x16_bf16 v[50:65], v[174:177], v[142:145], v[34:49]
	v_cvt_pk_bf16_f32 v140, v102, v103
	v_cvt_pk_bf16_f32 v141, v104, v105
	ds_read_b64_tr_b16 v[98:99], v203 offset:25600
	ds_read_b64_tr_b16 v[100:101], v203 offset:26112
	s_waitcnt lgkmcnt(11)
	v_mfma_f32_32x32x16_bf16 v[66:81], v[178:181], v[134:137], v[66:81]
	v_add_f32_e32 v102, v108, v114
	v_add_f32_e32 v102, v109, v102
	v_add_f32_e32 v102, v110, v102
	v_add_f32_e32 v114, v111, v102
	v_cvt_pk_bf16_f32 v130, v106, v107
	v_cvt_pk_bf16_f32 v131, v108, v109
	ds_read_b64_tr_b16 v[102:103], v203 offset:29696
	ds_read_b64_tr_b16 v[104:105], v203 offset:30208
	s_waitcnt lgkmcnt(12)
	v_mfma_f32_32x32x16_bf16 v[50:65], v[170:173], v[134:137], v[50:65]
	v_add_f32_e32 v106, v112, v114
	v_add_f32_e32 v106, v113, v106
	v_add_f32_e32 v106, v82, v106
	v_add_f32_e32 v114, v83, v106
	v_cvt_pk_bf16_f32 v132, v110, v111
	v_cvt_pk_bf16_f32 v133, v112, v113
	ds_read_b64_tr_b16 v[106:107], v203 offset:26624
	ds_read_b64_tr_b16 v[108:109], v203 offset:27136
	s_waitcnt lgkmcnt(13)
	v_mfma_f32_32x32x16_bf16 v[66:81], v[166:169], v[126:129], v[66:81]
	v_add_f32_e32 v110, v84, v114
	v_add_f32_e32 v110, v85, v110
	v_add_f32_e32 v110, v86, v110
	v_add_f32_e32 v110, v87, v110
	v_cvt_pk_bf16_f32 v122, v82, v83
	v_cvt_pk_bf16_f32 v123, v84, v85
	ds_read_b64_tr_b16 v[82:83], v203 offset:30720
	ds_read_b64_tr_b16 v[84:85], v203 offset:31232
	s_waitcnt lgkmcnt(14)
	v_mfma_f32_32x32x16_bf16 v[50:65], v[162:165], v[126:129], v[50:65]
	v_add_f32_e32 v110, v88, v110
	v_add_f32_e32 v110, v89, v110
	v_add_f32_e32 v110, v90, v110
	v_add_f32_e32 v110, v91, v110
	v_cvt_pk_bf16_f32 v124, v86, v87
	v_cvt_pk_bf16_f32 v125, v88, v89
	ds_read_b64_tr_b16 v[86:87], v203 offset:27648
	ds_read_b64_tr_b16 v[88:89], v203 offset:28160
	s_waitcnt lgkmcnt(14)
	v_mfma_f32_32x32x16_bf16 v[66:81], v[158:161], v[118:121], v[66:81]
	v_add_f32_e32 v110, v92, v110
	v_add_f32_e32 v110, v93, v110
	v_add_f32_e32 v110, v94, v110
	v_add_f32_e32 v110, v95, v110
	v_cvt_pk_bf16_f32 v114, v90, v91
	v_cvt_pk_bf16_f32 v115, v92, v93
	ds_read_b64_tr_b16 v[90:91], v203 offset:31744
	ds_read_b64_tr_b16 v[92:93], v203 offset:32256
	v_mfma_f32_32x32x16_bf16 v[50:65], v[154:157], v[118:121], v[50:65]
	v_add_f32_e32 v110, v96, v110
	v_add_f32_e32 v110, v97, v110
	v_cvt_pk_bf16_f32 v116, v94, v95
	v_cvt_pk_bf16_f32 v117, v96, v97
	s_add_i32 s98, s46, 0x2000
	s_mov_b32 s5, m0
	s_mov_b32 m0, s98
	s_nop 0
	global_load_lds_dwordx4 v189, s[100:101]
	s_mov_b32 m0, s5
	s_add_i32 s98, s47, 0x4000
	s_mov_b32 s5, m0
	s_mov_b32 m0, s98
	s_nop 0
	global_load_lds_dwordx4 v187, s[100:101]
	s_mov_b32 m0, s5
	v_add_f32_e32 v205, v190, v110
.Lf3_1_489:
	s_waitcnt lgkmcnt(14)
	v_mfma_f32_32x32x16_bf16 v[18:33], v[138:141], v[150:153], v[18:33]
	v_exp_f32_e32 v66, v66
	v_exp_f32_e32 v67, v67
	v_exp_f32_e32 v68, v68
	v_exp_f32_e32 v69, v69
	s_waitcnt lgkmcnt(12)
	v_mfma_f32_32x32x16_bf16 v[2:17], v[138:141], v[146:149], v[2:17]
	v_exp_f32_e32 v70, v70
	v_exp_f32_e32 v71, v71
	v_exp_f32_e32 v72, v72
	v_exp_f32_e32 v73, v73
	ds_read_b128 v[174:177], v202 offset:16384
	ds_read_b128 v[170:173], v202 offset:16896
	s_waitcnt lgkmcnt(12)
	v_mfma_f32_32x32x16_bf16 v[18:33], v[130:133], v[98:101], v[18:33]
	v_exp_f32_e32 v74, v74
	v_exp_f32_e32 v75, v75
	v_exp_f32_e32 v76, v76
	v_exp_f32_e32 v77, v77
	ds_read_b128 v[166:169], v202 offset:18432
	ds_read_b128 v[162:165], v202 offset:18944
	s_waitcnt lgkmcnt(12)
	v_mfma_f32_32x32x16_bf16 v[2:17], v[130:133], v[102:105], v[2:17]
	v_exp_f32_e32 v78, v78
	v_exp_f32_e32 v79, v79
	v_exp_f32_e32 v80, v80
	v_exp_f32_e32 v81, v81
	ds_read_b128 v[158:161], v202 offset:20480
	ds_read_b128 v[154:157], v202 offset:20992
	s_waitcnt lgkmcnt(12)
	v_mfma_f32_32x32x16_bf16 v[18:33], v[122:125], v[106:109], v[18:33]
	v_exp_f32_e32 v50, v50
	v_exp_f32_e32 v51, v51
	v_exp_f32_e32 v52, v52
	v_exp_f32_e32 v53, v53
	ds_read_b128 v[150:153], v202 offset:22528
	ds_read_b128 v[146:149], v202 offset:23040
	s_waitcnt lgkmcnt(12)
	v_mfma_f32_32x32x16_bf16 v[2:17], v[122:125], v[82:85], v[2:17]
	v_exp_f32_e32 v54, v54
	v_exp_f32_e32 v55, v55
	v_exp_f32_e32 v56, v56
	v_exp_f32_e32 v57, v57
	s_waitcnt lgkmcnt(10)
	v_mfma_f32_32x32x16_bf16 v[18:33], v[114:117], v[86:89], v[18:33]
	v_exp_f32_e32 v58, v58
	v_exp_f32_e32 v59, v59
	v_exp_f32_e32 v60, v60
	v_exp_f32_e32 v61, v61
	s_waitcnt lgkmcnt(8)
	v_mfma_f32_32x32x16_bf16 v[2:17], v[114:117], v[90:93], v[2:17]
	v_exp_f32_e32 v62, v62
	v_exp_f32_e32 v63, v63
	v_exp_f32_e32 v64, v64
	v_exp_f32_e32 v65, v65
	s_waitcnt vmcnt(2) lgkmcnt(0)
	s_barrier

.Lf3_2_485:
	ds_read_b64_tr_b16 v[178:179], v203 offset:32768
	ds_read_b64_tr_b16 v[180:181], v203 offset:33280
	s_waitcnt lgkmcnt(9)
	v_mfma_f32_32x32x16_bf16 v[98:113], v[174:177], v[142:145], v[34:49]
	v_add_f32_e32 v82, v66, v67
	v_add_f32_e32 v82, v68, v82
	v_add_f32_e32 v82, v69, v82
	v_add_f32_e32 v82, v70, v82
	v_add_f32_e32 v82, v71, v82
	v_cvt_pk_bf16_f32 v138, v66, v67
	v_cvt_pk_bf16_f32 v139, v68, v69
	ds_read_b64_tr_b16 v[174:175], v203 offset:36864
	ds_read_b64_tr_b16 v[176:177], v203 offset:37376
	v_add_f32_e32 v66, v72, v82
	s_waitcnt lgkmcnt(10)
	v_mfma_f32_32x32x16_bf16 v[82:97], v[170:173], v[142:145], v[34:49]
	v_add_f32_e32 v66, v73, v66
	v_add_f32_e32 v66, v74, v66
	v_add_f32_e32 v114, v75, v66
	v_cvt_pk_bf16_f32 v140, v70, v71
	v_cvt_pk_bf16_f32 v141, v72, v73
	ds_read_b64_tr_b16 v[66:67], v203 offset:33792
	ds_read_b64_tr_b16 v[68:69], v203 offset:34304
	s_waitcnt lgkmcnt(11)
	v_mfma_f32_32x32x16_bf16 v[98:113], v[166:169], v[134:137], v[98:113]
	v_add_f32_e32 v70, v76, v114
	v_add_f32_e32 v70, v77, v70
	v_add_f32_e32 v70, v78, v70
	v_add_f32_e32 v114, v79, v70
	v_cvt_pk_bf16_f32 v130, v74, v75
	v_cvt_pk_bf16_f32 v131, v76, v77
	ds_read_b64_tr_b16 v[70:71], v203 offset:37888
	ds_read_b64_tr_b16 v[72:73], v203 offset:38400
	s_waitcnt lgkmcnt(12)
	v_mfma_f32_32x32x16_bf16 v[82:97], v[162:165], v[134:137], v[82:97]
	v_add_f32_e32 v74, v80, v114
	v_add_f32_e32 v74, v81, v74
	v_add_f32_e32 v74, v50, v74
	v_add_f32_e32 v114, v51, v74
	v_cvt_pk_bf16_f32 v132, v78, v79
	v_cvt_pk_bf16_f32 v133, v80, v81
	ds_read_b64_tr_b16 v[74:75], v203 offset:34816
	ds_read_b64_tr_b16 v[76:77], v203 offset:35328
	s_waitcnt lgkmcnt(13)
	v_mfma_f32_32x32x16_bf16 v[98:113], v[158:161], v[126:129], v[98:113]
	v_add_f32_e32 v78, v52, v114
	v_add_f32_e32 v78, v53, v78
	v_add_f32_e32 v78, v54, v78
	v_add_f32_e32 v78, v55, v78
	v_cvt_pk_bf16_f32 v122, v50, v51
	v_cvt_pk_bf16_f32 v123, v52, v53
	ds_read_b64_tr_b16 v[50:51], v203 offset:38912
	ds_read_b64_tr_b16 v[52:53], v203 offset:39424
	s_waitcnt lgkmcnt(14)
	v_mfma_f32_32x32x16_bf16 v[82:97], v[154:157], v[126:129], v[82:97]
	v_add_f32_e32 v78, v56, v78
	v_add_f32_e32 v78, v57, v78
	v_add_f32_e32 v78, v58, v78
	v_add_f32_e32 v78, v59, v78
	v_cvt_pk_bf16_f32 v124, v54, v55
	v_cvt_pk_bf16_f32 v125, v56, v57
	ds_read_b64_tr_b16 v[54:55], v203 offset:35840
	ds_read_b64_tr_b16 v[56:57], v203 offset:36352
	s_waitcnt lgkmcnt(14)
	v_mfma_f32_32x32x16_bf16 v[98:113], v[150:153], v[118:121], v[98:113]
	v_add_f32_e32 v78, v60, v78
	v_add_f32_e32 v78, v61, v78
	v_add_f32_e32 v78, v62, v78
	v_add_f32_e32 v78, v63, v78
	v_cvt_pk_bf16_f32 v114, v58, v59
	v_cvt_pk_bf16_f32 v115, v60, v61
	ds_read_b64_tr_b16 v[58:59], v203 offset:39936
	ds_read_b64_tr_b16 v[60:61], v203 offset:40448
	v_mfma_f32_32x32x16_bf16 v[82:97], v[146:149], v[118:121], v[82:97]
	v_add_f32_e32 v78, v64, v78
	v_add_f32_e32 v78, v65, v78
	v_cvt_pk_bf16_f32 v116, v62, v63
	v_cvt_pk_bf16_f32 v117, v64, v65
	s_add_i32 s98, s46, 0x4000
	s_mov_b32 s5, m0
	s_mov_b32 m0, s98
	s_nop 0
	global_load_lds_dwordx4 v188, s[100:101]
	s_mov_b32 m0, s5
	s_add_i32 s98, s47, 0x0
	s_mov_b32 s5, m0
	s_mov_b32 m0, s98
	s_nop 0
	global_load_lds_dwordx4 v186, s[100:101]
	s_mov_b32 m0, s5
	v_add_f32_e32 v190, v205, v78
.Lf3_2_486:
	s_waitcnt lgkmcnt(14)
	v_mfma_f32_32x32x16_bf16 v[18:33], v[138:141], v[178:181], v[18:33]
	v_exp_f32_e32 v98, v98
	v_exp_f32_e32 v99, v99
	v_exp_f32_e32 v100, v100
	v_exp_f32_e32 v101, v101
	s_waitcnt lgkmcnt(12)
	v_mfma_f32_32x32x16_bf16 v[2:17], v[138:141], v[174:177], v[2:17]
	v_exp_f32_e32 v102, v102
	v_exp_f32_e32 v103, v103
	v_exp_f32_e32 v104, v104
	v_exp_f32_e32 v105, v105
	ds_read_b128 v[62:65], v202 offset:0
	ds_read_b128 v[174:177], v202 offset:512
	s_waitcnt lgkmcnt(12)
	v_mfma_f32_32x32x16_bf16 v[18:33], v[130:133], v[66:69], v[18:33]
	v_exp_f32_e32 v106, v106
	v_exp_f32_e32 v107, v107
	v_exp_f32_e32 v108, v108
	v_exp_f32_e32 v109, v109
	ds_read_b128 v[178:181], v202 offset:2048
	ds_read_b128 v[170:173], v202 offset:2560
	s_waitcnt lgkmcnt(12)
	v_mfma_f32_32x32x16_bf16 v[2:17], v[130:133], v[70:73], v[2:17]
	v_exp_f32_e32 v110, v110
	v_exp_f32_e32 v111, v111
	v_exp_f32_e32 v112, v112
	v_exp_f32_e32 v113, v113
	ds_read_b128 v[166:169], v202 offset:4096
	ds_read_b128 v[162:165], v202 offset:4608
	s_waitcnt lgkmcnt(12)
	v_mfma_f32_32x32x16_bf16 v[18:33], v[122:125], v[74:77], v[18:33]
	v_exp_f32_e32 v82, v82
	v_exp_f32_e32 v83, v83
	v_exp_f32_e32 v84, v84
	v_exp_f32_e32 v85, v85
	ds_read_b128 v[158:161], v202 offset:6144
	ds_read_b128 v[154:157], v202 offset:6656
	s_waitcnt lgkmcnt(12)
	v_mfma_f32_32x32x16_bf16 v[2:17], v[122:125], v[50:53], v[2:17]
	v_exp_f32_e32 v86, v86
	v_exp_f32_e32 v87, v87
	v_exp_f32_e32 v88, v88
	v_exp_f32_e32 v89, v89
	s_waitcnt lgkmcnt(10)
	v_mfma_f32_32x32x16_bf16 v[18:33], v[114:117], v[54:57], v[18:33]
	v_exp_f32_e32 v90, v90
	v_exp_f32_e32 v91, v91
	v_exp_f32_e32 v92, v92
	v_exp_f32_e32 v93, v93
	s_waitcnt lgkmcnt(8)
	v_mfma_f32_32x32x16_bf16 v[2:17], v[114:117], v[58:61], v[2:17]
	v_exp_f32_e32 v94, v94
	v_exp_f32_e32 v95, v95
	v_exp_f32_e32 v96, v96
	v_exp_f32_e32 v97, v97
	s_waitcnt vmcnt(2) lgkmcnt(0)
	s_barrier
.Lf3_2_488:
	ds_read_b64_tr_b16 v[150:151], v203 offset:40960
	ds_read_b64_tr_b16 v[152:153], v203 offset:41472
	s_waitcnt lgkmcnt(9)
	v_mfma_f32_32x32x16_bf16 v[66:81], v[62:65], v[142:145], v[34:49]
	v_add_f32_e32 v50, v98, v99
	v_add_f32_e32 v50, v100, v50
	v_add_f32_e32 v50, v101, v50
	v_add_f32_e32 v50, v102, v50
	v_add_f32_e32 v50, v103, v50
	v_cvt_pk_bf16_f32 v138, v98, v99
	v_cvt_pk_bf16_f32 v139, v100, v101
	ds_read_b64_tr_b16 v[146:147], v203 offset:45056
	ds_read_b64_tr_b16 v[148:149], v203 offset:45568
	v_add_f32_e32 v50, v104, v50
	v_add_f32_e32 v50, v105, v50
	v_add_f32_e32 v50, v106, v50
	v_add_f32_e32 v114, v107, v50
	s_waitcnt lgkmcnt(10)
	v_mfma_f32_32x32x16_bf16 v[50:65], v[174:177], v[142:145], v[34:49]
	v_cvt_pk_bf16_f32 v140, v102, v103
	v_cvt_pk_bf16_f32 v141, v104, v105
	ds_read_b64_tr_b16 v[98:99], v203 offset:41984
	ds_read_b64_tr_b16 v[100:101], v203 offset:42496
	s_waitcnt lgkmcnt(11)
	v_mfma_f32_32x32x16_bf16 v[66:81], v[178:181], v[134:137], v[66:81]
	v_add_f32_e32 v102, v108, v114
	v_add_f32_e32 v102, v109, v102
	v_add_f32_e32 v102, v110, v102
	v_add_f32_e32 v114, v111, v102
	v_cvt_pk_bf16_f32 v130, v106, v107
	v_cvt_pk_bf16_f32 v131, v108, v109
	ds_read_b64_tr_b16 v[102:103], v203 offset:46080
	ds_read_b64_tr_b16 v[104:105], v203 offset:46592
	s_waitcnt lgkmcnt(12)
	v_mfma_f32_32x32x16_bf16 v[50:65], v[170:173], v[134:137], v[50:65]
	v_add_f32_e32 v106, v112, v114
	v_add_f32_e32 v106, v113, v106
	v_add_f32_e32 v106, v82, v106
	v_add_f32_e32 v114, v83, v106
	v_cvt_pk_bf16_f32 v132, v110, v111
	v_cvt_pk_bf16_f32 v133, v112, v113
	ds_read_b64_tr_b16 v[106:107], v203 offset:43008
	ds_read_b64_tr_b16 v[108:109], v203 offset:43520
	s_waitcnt lgkmcnt(13)
	v_mfma_f32_32x32x16_bf16 v[66:81], v[166:169], v[126:129], v[66:81]
	v_add_f32_e32 v110, v84, v114
	v_add_f32_e32 v110, v85, v110
	v_add_f32_e32 v110, v86, v110
	v_add_f32_e32 v110, v87, v110
	v_cvt_pk_bf16_f32 v122, v82, v83
	v_cvt_pk_bf16_f32 v123, v84, v85
	ds_read_b64_tr_b16 v[82:83], v203 offset:47104
	ds_read_b64_tr_b16 v[84:85], v203 offset:47616
	s_waitcnt lgkmcnt(14)
	v_mfma_f32_32x32x16_bf16 v[50:65], v[162:165], v[126:129], v[50:65]
	v_add_f32_e32 v110, v88, v110
	v_add_f32_e32 v110, v89, v110
	v_add_f32_e32 v110, v90, v110
	v_add_f32_e32 v110, v91, v110
	v_cvt_pk_bf16_f32 v124, v86, v87
	v_cvt_pk_bf16_f32 v125, v88, v89
	ds_read_b64_tr_b16 v[86:87], v203 offset:44032
	ds_read_b64_tr_b16 v[88:89], v203 offset:44544
	s_waitcnt lgkmcnt(14)
	v_mfma_f32_32x32x16_bf16 v[66:81], v[158:161], v[118:121], v[66:81]
	v_add_f32_e32 v110, v92, v110
	v_add_f32_e32 v110, v93, v110
	v_add_f32_e32 v110, v94, v110
	v_add_f32_e32 v110, v95, v110
	v_cvt_pk_bf16_f32 v114, v90, v91
	v_cvt_pk_bf16_f32 v115, v92, v93
	ds_read_b64_tr_b16 v[90:91], v203 offset:48128
	ds_read_b64_tr_b16 v[92:93], v203 offset:48640
	v_mfma_f32_32x32x16_bf16 v[50:65], v[154:157], v[118:121], v[50:65]
	v_add_f32_e32 v110, v96, v110
	v_add_f32_e32 v110, v97, v110
	v_cvt_pk_bf16_f32 v116, v94, v95
	v_cvt_pk_bf16_f32 v117, v96, v97
	s_add_i32 s98, s46, 0x0
	s_mov_b32 s5, m0
	s_mov_b32 m0, s98
	s_nop 0
	global_load_lds_dwordx4 v189, s[100:101]
	s_mov_b32 m0, s5
	s_add_i32 s98, s47, 0x2000
	s_mov_b32 s5, m0
	s_mov_b32 m0, s98
	s_nop 0
	global_load_lds_dwordx4 v187, s[100:101]
	s_mov_b32 m0, s5
	v_add_f32_e32 v205, v190, v110
.Lf3_2_489:
	s_waitcnt lgkmcnt(14)
	v_mfma_f32_32x32x16_bf16 v[18:33], v[138:141], v[150:153], v[18:33]
	v_exp_f32_e32 v66, v66
	v_exp_f32_e32 v67, v67
	v_exp_f32_e32 v68, v68
	v_exp_f32_e32 v69, v69
	s_waitcnt lgkmcnt(12)
	v_mfma_f32_32x32x16_bf16 v[2:17], v[138:141], v[146:149], v[2:17]
	v_exp_f32_e32 v70, v70
	v_exp_f32_e32 v71, v71
	v_exp_f32_e32 v72, v72
	v_exp_f32_e32 v73, v73
	ds_read_b128 v[174:177], v202 offset:8192
	ds_read_b128 v[170:173], v202 offset:8704
	s_waitcnt lgkmcnt(12)
	v_mfma_f32_32x32x16_bf16 v[18:33], v[130:133], v[98:101], v[18:33]
	v_exp_f32_e32 v74, v74
	v_exp_f32_e32 v75, v75
	v_exp_f32_e32 v76, v76
	v_exp_f32_e32 v77, v77
	ds_read_b128 v[166:169], v202 offset:10240
	ds_read_b128 v[162:165], v202 offset:10752
	s_waitcnt lgkmcnt(12)
	v_mfma_f32_32x32x16_bf16 v[2:17], v[130:133], v[102:105], v[2:17]
	v_exp_f32_e32 v78, v78
	v_exp_f32_e32 v79, v79
	v_exp_f32_e32 v80, v80
	v_exp_f32_e32 v81, v81
	ds_read_b128 v[158:161], v202 offset:12288
	ds_read_b128 v[154:157], v202 offset:12800
	s_waitcnt lgkmcnt(12)
	v_mfma_f32_32x32x16_bf16 v[18:33], v[122:125], v[106:109], v[18:33]
	v_exp_f32_e32 v50, v50
	v_exp_f32_e32 v51, v51
	v_exp_f32_e32 v52, v52
	v_exp_f32_e32 v53, v53
	ds_read_b128 v[150:153], v202 offset:14336
	ds_read_b128 v[146:149], v202 offset:14848
	s_waitcnt lgkmcnt(12)
	v_mfma_f32_32x32x16_bf16 v[2:17], v[122:125], v[82:85], v[2:17]
	v_exp_f32_e32 v54, v54
	v_exp_f32_e32 v55, v55
	v_exp_f32_e32 v56, v56
	v_exp_f32_e32 v57, v57
	s_waitcnt lgkmcnt(10)
	v_mfma_f32_32x32x16_bf16 v[18:33], v[114:117], v[86:89], v[18:33]
	v_exp_f32_e32 v58, v58
	v_exp_f32_e32 v59, v59
	v_exp_f32_e32 v60, v60
	v_exp_f32_e32 v61, v61
	s_waitcnt lgkmcnt(8)
	v_mfma_f32_32x32x16_bf16 v[2:17], v[114:117], v[90:93], v[2:17]
	v_exp_f32_e32 v62, v62
	v_exp_f32_e32 v63, v63
	v_exp_f32_e32 v64, v64
	v_exp_f32_e32 v65, v65
	s_waitcnt vmcnt(2) lgkmcnt(0)
	s_barrier
.Lf3_2_491:
	s_add_u32 s100, s100, s42
	s_addc_u32 s101, s101, s43
	s_add_i32 s5, s10, 6
	s_cmp_ge_u32 s5, s19
	s_cbranch_scc1 .Lfast3_exit
	s_mov_b32 s10, s5
	s_add_i32 s5, s5, 4
	s_cmp_lt_u32 s5, s19
	s_cbranch_scc1 .Lfast3
	s_branch .Lfast_485
.Lfast3_exit:
	s_add_i32 s10, s10, 4
	s_movk_i32 s11, 0x4000
	s_mov_b32 s14, 0
	s_movk_i32 s50, 0x2000
	s_movk_i32 s25, 0x4000
	s_branch .LBB0_500
